# same composite with the P4 row loop made generic in grid size (row-index bounds instead of a hard-coded rows-per-wave)
# speedup vs baseline: 1.0192x; 1.0192x over previous
; #define LAS __attribute__((address_space(3)))
; template <int MODE>
; __device__ __forceinline__ void step64(St& S, const bf16x8 (&qf)[4], int t, int qpos0, bool diag, bool first, float cq, float cfar, const LAS float* tab,
;                                        const LAS unsigned char* buf, unsigned vaddr, int r32, int hi) {
;     ...
;         const float nm = cq - S.m;
; #pragma unroll
;         for (int g = 0; g < 4; ++g) { const f32x4 c0 = *(const LAS f32x4*)(tab + t * 64 + 8 * g + 4 * hi), c1 = *(const LAS f32x4*)(tab + t * 64 + 32 + 8 * g + 4 * hi);
; #pragma unroll
;             for (int e = 0; e < 4; ++e) { sa[4 * g + e] = nm - c0[e]; sb[4 * g + e] = nm - c1[e]; } }
;     ...
; #pragma unroll
;     for (int r = 0; r < 16; ++r) { sa[r] = __builtin_amdgcn_exp2f(sa[r]); sb[r] = __builtin_amdgcn_exp2f(sb[r]); }
;     asm volatile("s_waitcnt lgkmcnt(0)" ::: "memory");
;     __builtin_amdgcn_sched_barrier(0);
;     u32x4 pa0, pa1, pb0, pb1;
;     pa0.x = pk2(sa[0], sa[1]); pa0.y = pk2(sa[2], sa[3]); pa0.z = pk2(sa[4], sa[5]); pa0.w = pk2(sa[6], sa[7]);
;     pa1.x = pk2(sa[8], sa[9]); pa1.y = pk2(sa[10], sa[11]); pa1.z = pk2(sa[12], sa[13]); pa1.w = pk2(sa[14], sa[15]);
;     pb0.x = pk2(sb[0], sb[1]); pb0.y = pk2(sb[2], sb[3]); pb0.z = pk2(sb[4], sb[5]); pb0.w = pk2(sb[6], sb[7]);
;     pb1.x = pk2(sb[8], sb[9]); pb1.y = pk2(sb[10], sb[11]); pb1.z = pk2(sb[12], sb[13]); pb1.w = pk2(sb[14], sb[15]);
;     ...
;     S.o0 = __builtin_amdgcn_mfma_f32_32x32x16_bf16(ATT_VF(0), ATT_PF(pa0), S.o0, 0, 0, 0);
;     S.o1 = __builtin_amdgcn_mfma_f32_32x32x16_bf16(ATT_VF(2), ATT_PF(pa0), S.o1, 0, 0, 0);
;     S.o0 = __builtin_amdgcn_mfma_f32_32x32x16_bf16(ATT_VF(1), ATT_PF(pa1), S.o0, 0, 0, 0);
;     S.o1 = __builtin_amdgcn_mfma_f32_32x32x16_bf16(ATT_VF(3), ATT_PF(pa1), S.o1, 0, 0, 0);
;     S.o0 = __builtin_amdgcn_mfma_f32_32x32x16_bf16(ATT_VF(4), ATT_PF(pb0), S.o0, 0, 0, 0);
;     S.o1 = __builtin_amdgcn_mfma_f32_32x32x16_bf16(ATT_VF(6), ATT_PF(pb0), S.o1, 0, 0, 0);
;     S.o0 = __builtin_amdgcn_mfma_f32_32x32x16_bf16(ATT_VF(5), ATT_PF(pb1), S.o0, 0, 0, 0);
;     S.o1 = __builtin_amdgcn_mfma_f32_32x32x16_bf16(ATT_VF(7), ATT_PF(pb1), S.o1, 0, 0, 0);
;     ...
;     float l0 = 0.f, l1 = 0.f, l2 = 0.f, l3 = 0.f;
; #pragma unroll
;     for (int r = 0; r < 16; r += 2) { l0 += sa[r]; l1 += sa[r + 1]; l2 += sb[r]; l3 += sb[r + 1]; }
;     S.l += (l0 + l1) + (l2 + l3);
.Lm1_pv:
	v_exp_f32_e32 v48, v48
	v_exp_f32_e32 v49, v49
	v_exp_f32_e32 v50, v50
	v_exp_f32_e32 v51, v51
	v_exp_f32_e32 v52, v52
	v_exp_f32_e32 v53, v53
	v_exp_f32_e32 v54, v54
	v_exp_f32_e32 v55, v55
	v_cvt_pk_bf16_f32 v152, v48, v49
	v_cvt_pk_bf16_f32 v153, v50, v51
	v_cvt_pk_bf16_f32 v154, v52, v53
	v_cvt_pk_bf16_f32 v155, v54, v55
	v_exp_f32_e32 v56, v56
	v_exp_f32_e32 v57, v57
	v_mfma_f32_32x32x16_bf16 v[32:47], v[112:115], v[152:155], v[32:47]
	v_exp_f32_e32 v58, v58
	v_exp_f32_e32 v59, v59
	v_exp_f32_e32 v60, v60
	v_exp_f32_e32 v61, v61
	v_exp_f32_e32 v62, v62
	v_exp_f32_e32 v63, v63
	v_mfma_f32_32x32x16_bf16 v[16:31], v[108:111], v[152:155], v[16:31]
	v_cvt_pk_bf16_f32 v156, v56, v57
	v_cvt_pk_bf16_f32 v157, v58, v59
	v_cvt_pk_bf16_f32 v158, v60, v61
	v_cvt_pk_bf16_f32 v159, v62, v63
	v_add_f32_e32 v0, v48, v50
	v_add_f32_e32 v0, v0, v52
	v_add_f32_e32 v14, v49, v51
	v_add_f32_e32 v14, v14, v53
	v_mfma_f32_32x32x16_bf16 v[32:47], v[104:107], v[156:159], v[32:47]
	v_exp_f32_e32 v64, v64
	v_exp_f32_e32 v65, v65
	v_exp_f32_e32 v66, v66
	v_exp_f32_e32 v67, v67
	v_exp_f32_e32 v68, v68
	v_exp_f32_e32 v69, v69
	v_exp_f32_e32 v70, v70
	v_exp_f32_e32 v71, v71
	v_mfma_f32_32x32x16_bf16 v[16:31], v[100:103], v[156:159], v[16:31]
	v_cvt_pk_bf16_f32 v160, v64, v65
	v_cvt_pk_bf16_f32 v161, v66, v67
	v_cvt_pk_bf16_f32 v162, v68, v69
	v_cvt_pk_bf16_f32 v163, v70, v71
	v_add_f32_e32 v0, v0, v54
	v_add_f32_e32 v0, v0, v56
	v_add_f32_e32 v14, v14, v55
	v_add_f32_e32 v14, v14, v57
	v_mfma_f32_32x32x16_bf16 v[32:47], v[96:99], v[160:163], v[32:47]
	v_exp_f32_e32 v72, v72
	v_exp_f32_e32 v73, v73
	v_exp_f32_e32 v74, v74
	v_exp_f32_e32 v75, v75
	v_exp_f32_e32 v76, v76
	v_exp_f32_e32 v77, v77
	v_exp_f32_e32 v78, v78
	v_exp_f32_e32 v79, v79
	v_mfma_f32_32x32x16_bf16 v[16:31], v[10:13], v[160:163], v[16:31]
	v_cvt_pk_bf16_f32 v234, v72, v73
	v_cvt_pk_bf16_f32 v235, v74, v75
	v_cvt_pk_bf16_f32 v236, v76, v77
	v_cvt_pk_bf16_f32 v237, v78, v79
	v_add_f32_e32 v0, v0, v58
	v_add_f32_e32 v0, v0, v60
	v_add_f32_e32 v0, v0, v62
	v_add_f32_e32 v14, v14, v59
	v_add_f32_e32 v14, v14, v61
	v_add_f32_e32 v14, v14, v63
	v_mfma_f32_32x32x16_bf16 v[32:47], v[6:9], v[234:237], v[32:47]
	v_add_f32_e32 v15, v64, v66
	v_add_f32_e32 v15, v15, v68
	v_add_f32_e32 v15, v15, v70
	v_add_f32_e32 v15, v15, v72
	v_add_f32_e32 v151, v65, v67
	v_add_f32_e32 v151, v151, v69
	v_add_f32_e32 v151, v151, v71
	v_add_f32_e32 v151, v151, v73
	v_mfma_f32_32x32x16_bf16 v[16:31], v[2:5], v[234:237], v[16:31]
	v_add_f32_e32 v15, v15, v74
	v_add_f32_e32 v15, v15, v76
	v_add_f32_e32 v15, v15, v78
	v_add_f32_e32 v151, v151, v75
	v_add_f32_e32 v151, v151, v77
	v_add_f32_e32 v151, v151, v79
	v_add_f32_e32 v0, v0, v14
	v_add_f32_e32 v15, v15, v151
	v_add_f32_e32 v0, v0, v15
	v_add_f32_e32 v149, v149, v0
	s_cmp_eq_u32 s22, 0
	s_cbranch_scc1 .Lm1_end
	v_sub_f32_e32 v151, v142, v150
	s_waitcnt lgkmcnt(0)
	v_sub_f32_e32 v48, v151, v186
	v_sub_f32_e32 v49, v151, v187
	v_sub_f32_e32 v50, v151, v188
	v_sub_f32_e32 v51, v151, v189
	v_sub_f32_e32 v52, v151, v190
	v_sub_f32_e32 v53, v151, v191
	v_sub_f32_e32 v54, v151, v192
	v_sub_f32_e32 v55, v151, v193
	v_sub_f32_e32 v56, v151, v194
	v_sub_f32_e32 v57, v151, v195
	v_sub_f32_e32 v58, v151, v196
	v_sub_f32_e32 v59, v151, v197
	v_sub_f32_e32 v60, v151, v198
	v_sub_f32_e32 v61, v151, v199
	v_sub_f32_e32 v62, v151, v200
	v_sub_f32_e32 v63, v151, v201
	v_sub_f32_e32 v64, v151, v202
	v_sub_f32_e32 v65, v151, v203
	v_sub_f32_e32 v66, v151, v204
	v_sub_f32_e32 v67, v151, v205
	v_sub_f32_e32 v68, v151, v206
	v_sub_f32_e32 v69, v151, v207
	v_sub_f32_e32 v70, v151, v208
	v_sub_f32_e32 v71, v151, v209
	v_sub_f32_e32 v72, v151, v210
	v_sub_f32_e32 v73, v151, v211
	v_sub_f32_e32 v74, v151, v212
	v_sub_f32_e32 v75, v151, v213
	v_sub_f32_e32 v76, v151, v214
	v_sub_f32_e32 v77, v151, v215
	v_sub_f32_e32 v78, v151, v216
	v_sub_f32_e32 v79, v151, v217

; __device__ __forceinline__ float bf_lo(unsigned w) { return __uint_as_float(w << 16); }
; __device__ __forceinline__ float bf_hi(unsigned w) { return __uint_as_float(w & 0xffff0000u); }
; __device__ __forceinline__ void phase4(const Params& P, int lane, int wave) {
;     const int gw = blockIdx.x * 8 + wave, NGW = gridDim.x * 8;
;     const bf16_t* mo = (const bf16_t*)(P.ws + WS_SEG);
;     f32x4 g4[4];
; #pragma unroll
;     for (int j = 0; j < 4; ++j) g4[j] = *(const f32x4*)(P.fgain + 4 * lane + 256 * j);
;     f32x4 v[4]; u32x2 mv[4];
;     int m = gw;
;     if (m < MT) {
;         const float* xrow = (m < MP) ? P.xp + (size_t)m * 1024 : P.xs + (size_t)(m - MP) * 1024;
; #pragma unroll
;         for (int j = 0; j < 4; ++j) { v[j] = *(const f32x4*)(xrow + 4 * lane + 256 * j); mv[j] = *(const u32x2*)(mo + (size_t)m * 1024 + 4 * lane + 256 * j); }
;     }
;     for (; m < MT; m += NGW) {
;         f32x4 r[4]; float ss = 0.f;
; #pragma unroll
;         for (int j = 0; j < 4; ++j) {
;             r[j][0] = v[j][0] + bf_lo(mv[j].x); r[j][1] = v[j][1] + bf_hi(mv[j].x); r[j][2] = v[j][2] + bf_lo(mv[j].y); r[j][3] = v[j][3] + bf_hi(mv[j].y);
;             ss += (r[j][0] * r[j][0] + r[j][1] * r[j][1]) + (r[j][2] * r[j][2] + r[j][3] * r[j][3]);
;         }
;         const int mn = m + NGW;
;         if (mn < MT) {
;             const float* xrow = (mn < MP) ? P.xp + (size_t)mn * 1024 : P.xs + (size_t)(mn - MP) * 1024;
; #pragma unroll
;             for (int j = 0; j < 4; ++j) { v[j] = *(const f32x4*)(xrow + 4 * lane + 256 * j); mv[j] = *(const u32x2*)(mo + (size_t)mn * 1024 + 4 * lane + 256 * j); }
;         }
;         ss = wave_sum(ss);
.LBB0_793:
	s_or_b64 exec, exec, s[0:1]
	v_readlane_b32 s0, v241, 12
	v_readlane_b32 s1, v241, 13
	s_andn2_b64 vcc, exec, s[0:1]
	s_waitcnt lgkmcnt(0)
	s_barrier
	s_cbranch_vccnz .LBB0_806
	v_mbcnt_hi_u32_b32 v82, -1, v179
	v_lshlrev_b32_e32 v80, 4, v82
	v_lshlrev_b32_e32 v81, 3, v82
	global_load_dwordx4 v[0:3], v80, s[88:89]
	global_load_dwordx4 v[4:7], v80, s[88:89] offset:1024
	global_load_dwordx4 v[8:11], v80, s[88:89] offset:2048
	global_load_dwordx4 v[12:15], v80, s[88:89] offset:3072
	v_xor_b32_e32 v72, 1, v82
	v_lshlrev_b32_e32 v72, 2, v72
	v_xor_b32_e32 v73, 2, v82
	v_lshlrev_b32_e32 v73, 2, v73
	v_xor_b32_e32 v74, 4, v82
	v_lshlrev_b32_e32 v74, 2, v74
	v_xor_b32_e32 v75, 8, v82
	v_lshlrev_b32_e32 v75, 2, v75
	v_xor_b32_e32 v76, 16, v82
	v_lshlrev_b32_e32 v76, 2, v76
	v_xor_b32_e32 v77, 32, v82
	v_lshlrev_b32_e32 v77, 2, v77
	v_mov_b32_e32 v70, 0x358637bd
	v_mov_b32_e32 v71, 0x260
	s_mov_b32 s2, 0xf800000
	v_readlane_b32 s8, v241, 10
	s_mov_b32 s11, s8
	s_mov_b32 s16, s11
	s_lshl_b32 s17, s16, 11
	s_add_u32 s14, s4, s17
	s_addc_u32 s15, s5, 0
	s_add_i32 s18, s16, 0xffff0000
	s_cmp_lt_u32 s16, 0x10000
	s_cselect_b32 s18, s16, s18
	s_cselect_b32 s12, s68, s70
	s_cselect_b32 s13, s69, s71
	s_lshr_b32 s19, s18, 20
	s_lshl_b32 s18, s18, 12
	s_add_u32 s12, s12, s18
	s_addc_u32 s13, s13, s19
	global_load_dwordx4 v[16:19], v80, s[12:13]
	global_load_dwordx4 v[20:23], v80, s[12:13] offset:1024
	global_load_dwordx4 v[24:27], v80, s[12:13] offset:2048
	global_load_dwordx4 v[28:31], v80, s[12:13] offset:3072
	global_load_dwordx2 v[32:33], v81, s[14:15]
	global_load_dwordx2 v[34:35], v81, s[14:15] offset:512
	global_load_dwordx2 v[36:37], v81, s[14:15] offset:1024
	global_load_dwordx2 v[38:39], v81, s[14:15] offset:1536
	s_add_i32 s20, s11, s84
	s_cmp_lt_u32 s20, 0x10100
	s_cselect_b32 s20, s20, s11
	s_mov_b32 s16, s20
	s_lshl_b32 s17, s16, 11
	s_add_u32 s14, s4, s17
	s_addc_u32 s15, s5, 0
	s_add_i32 s18, s16, 0xffff0000
	s_cmp_lt_u32 s16, 0x10000
	s_cselect_b32 s18, s16, s18
	s_cselect_b32 s12, s68, s70
	s_cselect_b32 s13, s69, s71
	s_lshr_b32 s19, s18, 20
	s_lshl_b32 s18, s18, 12
	s_add_u32 s12, s12, s18
	s_addc_u32 s13, s13, s19
	global_load_dwordx4 v[40:43], v80, s[12:13]
	global_load_dwordx4 v[44:47], v80, s[12:13] offset:1024
	global_load_dwordx4 v[48:51], v80, s[12:13] offset:2048
	global_load_dwordx4 v[52:55], v80, s[12:13] offset:3072
	global_load_dwordx2 v[56:57], v81, s[14:15]
	global_load_dwordx2 v[58:59], v81, s[14:15] offset:512
	global_load_dwordx2 v[60:61], v81, s[14:15] offset:1024
	global_load_dwordx2 v[62:63], v81, s[14:15] offset:1536
.Lp4_loop:
	s_lshl_b32 s20, s84, 1
	s_add_i32 s20, s11, s20
	s_cmp_lt_u32 s20, 0x10100
	s_cselect_b32 s20, s20, s11
	s_mov_b32 s16, s20
	s_lshl_b32 s17, s16, 11
	s_add_u32 s14, s4, s17
	s_addc_u32 s15, s5, 0
	s_add_i32 s18, s16, 0xffff0000
	s_cmp_lt_u32 s16, 0x10000
	s_cselect_b32 s18, s16, s18
	s_cselect_b32 s12, s68, s70
	s_cselect_b32 s13, s69, s71
	s_lshr_b32 s19, s18, 20
	s_lshl_b32 s18, s18, 12
	s_add_u32 s12, s12, s18
	s_addc_u32 s13, s13, s19
	global_load_dwordx4 v[88:91], v80, s[12:13]
	global_load_dwordx4 v[92:95], v80, s[12:13] offset:1024
	global_load_dwordx4 v[96:99], v80, s[12:13] offset:2048
	global_load_dwordx4 v[100:103], v80, s[12:13] offset:3072
	global_load_dwordx2 v[104:105], v81, s[14:15]
	global_load_dwordx2 v[106:107], v81, s[14:15] offset:512
	global_load_dwordx2 v[108:109], v81, s[14:15] offset:1024
	global_load_dwordx2 v[110:111], v81, s[14:15] offset:1536
	s_lshr_b32 s19, s11, 20
	s_lshl_b32 s18, s11, 12
	s_add_u32 s0, s90, s18
	s_addc_u32 s1, s91, s19
	s_waitcnt vmcnt(16)
	v_lshlrev_b32_e32 v64, 16, v32
	v_and_b32_e32 v65, 0xffff0000, v32
	v_add_f32_e32 v16, v16, v64
	v_add_f32_e32 v17, v17, v65
	v_lshlrev_b32_e32 v64, 16, v33
	v_and_b32_e32 v65, 0xffff0000, v33
	v_add_f32_e32 v18, v18, v64
	v_add_f32_e32 v19, v19, v65
	v_lshlrev_b32_e32 v64, 16, v34
	v_and_b32_e32 v65, 0xffff0000, v34
	v_add_f32_e32 v20, v20, v64
	v_add_f32_e32 v21, v21, v65
	v_lshlrev_b32_e32 v64, 16, v35
	v_and_b32_e32 v65, 0xffff0000, v35
	v_add_f32_e32 v22, v22, v64
	v_add_f32_e32 v23, v23, v65
	v_lshlrev_b32_e32 v64, 16, v36
	v_and_b32_e32 v65, 0xffff0000, v36
	v_add_f32_e32 v24, v24, v64
	v_add_f32_e32 v25, v25, v65
	v_lshlrev_b32_e32 v64, 16, v37
	v_and_b32_e32 v65, 0xffff0000, v37
	v_add_f32_e32 v26, v26, v64
	v_add_f32_e32 v27, v27, v65
	v_lshlrev_b32_e32 v64, 16, v38
	v_and_b32_e32 v65, 0xffff0000, v38
	v_add_f32_e32 v28, v28, v64
	v_add_f32_e32 v29, v29, v65
	v_lshlrev_b32_e32 v64, 16, v39
	v_and_b32_e32 v65, 0xffff0000, v39
	v_add_f32_e32 v30, v30, v64
	v_add_f32_e32 v31, v31, v65
	v_mul_f32_e32 v64, v16, v16
	v_mul_f32_e32 v65, v17, v17
	v_mul_f32_e32 v66, v18, v18
	v_mul_f32_e32 v67, v19, v19
	v_add_f32_e32 v64, v64, v65
	v_add_f32_e32 v66, v66, v67
	v_add_f32_e32 v68, v64, v66
	v_mul_f32_e32 v64, v20, v20
	v_mul_f32_e32 v65, v21, v21
	v_mul_f32_e32 v66, v22, v22
	v_mul_f32_e32 v67, v23, v23
	v_add_f32_e32 v64, v64, v65
	v_add_f32_e32 v66, v66, v67
	v_add_f32_e32 v64, v64, v66
	v_add_f32_e32 v68, v68, v64
	v_mul_f32_e32 v64, v24, v24
	v_mul_f32_e32 v65, v25, v25
	v_mul_f32_e32 v66, v26, v26
	v_mul_f32_e32 v67, v27, v27
	v_add_f32_e32 v64, v64, v65
	v_add_f32_e32 v66, v66, v67
	v_add_f32_e32 v64, v64, v66
	v_add_f32_e32 v68, v68, v64
	v_mul_f32_e32 v64, v28, v28
	v_mul_f32_e32 v65, v29, v29
	v_mul_f32_e32 v66, v30, v30
	v_mul_f32_e32 v67, v31, v31
	v_add_f32_e32 v64, v64, v65
	v_add_f32_e32 v66, v66, v67
	v_add_f32_e32 v64, v64, v66
	v_add_f32_e32 v68, v68, v64
	ds_bpermute_b32 v69, v72, v68
	s_waitcnt lgkmcnt(0)
	v_add_f32_e32 v68, v68, v69
	ds_bpermute_b32 v69, v73, v68
	s_waitcnt lgkmcnt(0)
; __device__ __forceinline__ void phase4(const Params& P, int lane, int wave) {
;     ...
;         ss = wave_sum(ss);
;         const float rstd = 1.0f / sqrtf(ss * (1.0f / 1024.0f) + RMS_EPS);
;         float* row = P.out + (size_t)m * 1024;
; #pragma unroll
;         for (int j = 0; j < 4; ++j) *(f32x4*)(row + 4 * lane + 256 * j) = r[j] * rstd * g4[j];
;     }
	v_add_f32_e32 v68, v68, v69
	ds_bpermute_b32 v69, v74, v68
	s_waitcnt lgkmcnt(0)
	v_add_f32_e32 v68, v68, v69
	ds_bpermute_b32 v69, v75, v68
	s_waitcnt lgkmcnt(0)
	v_add_f32_e32 v68, v68, v69
	ds_bpermute_b32 v69, v76, v68
	s_waitcnt lgkmcnt(0)
	v_add_f32_e32 v68, v68, v69
	ds_bpermute_b32 v69, v77, v68
	s_waitcnt lgkmcnt(0)
	v_add_f32_e32 v68, v68, v69
	v_fmamk_f32 v68, v68, 0x3a800000, v70
	v_mul_f32_e32 v69, 0x4f800000, v68
	v_cmp_gt_f32_e32 vcc, s2, v68
	s_nop 1
	v_cndmask_b32_e32 v68, v68, v69, vcc
	v_sqrt_f32_e32 v69, v68
	s_nop 0
	v_add_u32_e32 v64, -1, v69
	v_fma_f32 v65, -v64, v69, v68
	v_cmp_ge_f32_e64 s[6:7], 0, v65
	v_add_u32_e32 v65, 1, v69
	s_nop 0
	v_cndmask_b32_e64 v64, v69, v64, s[6:7]
	v_fma_f32 v69, -v65, v69, v68
	v_cmp_lt_f32_e64 s[6:7], 0, v69
	s_nop 1
	v_cndmask_b32_e64 v69, v64, v65, s[6:7]
	v_mul_f32_e32 v64, 0x37800000, v69
	v_cndmask_b32_e32 v69, v69, v64, vcc
	v_cmp_class_f32_e32 vcc, v68, v71
	s_nop 1
	v_cndmask_b32_e32 v68, v69, v68, vcc
	v_div_scale_f32 v69, s[6:7], v68, v68, 1.0
	v_rcp_f32_e32 v64, v69
	s_nop 0
	v_fma_f32 v65, -v69, v64, 1.0
	v_fmac_f32_e32 v64, v65, v64
	v_div_scale_f32 v65, vcc, 1.0, v68, 1.0
	v_mul_f32_e32 v66, v65, v64
	v_fma_f32 v67, -v69, v66, v65
	v_fmac_f32_e32 v66, v67, v64
	v_fma_f32 v69, -v69, v66, v65
	v_div_fmas_f32 v69, v69, v64, v66
	v_div_fixup_f32 v68, v69, v68, 1.0
	v_mul_f32_e32 v16, v16, v68
	v_mul_f32_e32 v17, v17, v68
	v_mul_f32_e32 v18, v18, v68
	v_mul_f32_e32 v19, v19, v68
	v_mul_f32_e32 v16, v0, v16
	v_mul_f32_e32 v17, v1, v17
	v_mul_f32_e32 v18, v2, v18
	v_mul_f32_e32 v19, v3, v19
	global_store_dwordx4 v80, v[16:19], s[0:1]
	v_mul_f32_e32 v20, v20, v68
	v_mul_f32_e32 v21, v21, v68
	v_mul_f32_e32 v22, v22, v68
	v_mul_f32_e32 v23, v23, v68
	v_mul_f32_e32 v20, v4, v20
	v_mul_f32_e32 v21, v5, v21
	v_mul_f32_e32 v22, v6, v22
	v_mul_f32_e32 v23, v7, v23
	global_store_dwordx4 v80, v[20:23], s[0:1] offset:1024
	v_mul_f32_e32 v24, v24, v68
	v_mul_f32_e32 v25, v25, v68
	v_mul_f32_e32 v26, v26, v68
	v_mul_f32_e32 v27, v27, v68
	v_mul_f32_e32 v24, v8, v24
	v_mul_f32_e32 v25, v9, v25
	v_mul_f32_e32 v26, v10, v26
	v_mul_f32_e32 v27, v11, v27
	global_store_dwordx4 v80, v[24:27], s[0:1] offset:2048
	v_mul_f32_e32 v28, v28, v68
	v_mul_f32_e32 v29, v29, v68
	v_mul_f32_e32 v30, v30, v68
	v_mul_f32_e32 v31, v31, v68
	v_mul_f32_e32 v28, v12, v28
	v_mul_f32_e32 v29, v13, v29
	v_mul_f32_e32 v30, v14, v30
	v_mul_f32_e32 v31, v15, v31
	global_store_dwordx4 v80, v[28:31], s[0:1] offset:3072
	s_add_i32 s11, s11, s84
	s_cmp_ge_u32 s11, 0x10100
	s_cbranch_scc1 .LBB0_806
	s_lshl_b32 s20, s84, 1
	s_add_i32 s20, s11, s20
	s_cmp_lt_u32 s20, 0x10100
	s_cselect_b32 s20, s20, s11
	s_mov_b32 s16, s20
	s_lshl_b32 s17, s16, 11
	s_add_u32 s14, s4, s17
	s_addc_u32 s15, s5, 0
	s_add_i32 s18, s16, 0xffff0000
	s_cmp_lt_u32 s16, 0x10000
	s_cselect_b32 s18, s16, s18
	s_cselect_b32 s12, s68, s70
	s_cselect_b32 s13, s69, s71
	s_lshr_b32 s19, s18, 20
	s_lshl_b32 s18, s18, 12
	s_add_u32 s12, s12, s18
	s_addc_u32 s13, s13, s19
	global_load_dwordx4 v[16:19], v80, s[12:13]
	global_load_dwordx4 v[20:23], v80, s[12:13] offset:1024
	global_load_dwordx4 v[24:27], v80, s[12:13] offset:2048
	global_load_dwordx4 v[28:31], v80, s[12:13] offset:3072
	global_load_dwordx2 v[32:33], v81, s[14:15]
	global_load_dwordx2 v[34:35], v81, s[14:15] offset:512
	global_load_dwordx2 v[36:37], v81, s[14:15] offset:1024
	global_load_dwordx2 v[38:39], v81, s[14:15] offset:1536
	s_lshr_b32 s19, s11, 20
	s_lshl_b32 s18, s11, 12
	s_add_u32 s0, s90, s18
	s_addc_u32 s1, s91, s19
	s_waitcnt vmcnt(16)
	v_lshlrev_b32_e32 v64, 16, v56
	v_and_b32_e32 v65, 0xffff0000, v56
	v_add_f32_e32 v40, v40, v64
	v_add_f32_e32 v41, v41, v65
	v_lshlrev_b32_e32 v64, 16, v57
	v_and_b32_e32 v65, 0xffff0000, v57
	v_add_f32_e32 v42, v42, v64
	v_add_f32_e32 v43, v43, v65
	v_lshlrev_b32_e32 v64, 16, v58
	v_and_b32_e32 v65, 0xffff0000, v58
	v_add_f32_e32 v44, v44, v64
	v_add_f32_e32 v45, v45, v65
	v_lshlrev_b32_e32 v64, 16, v59
	v_and_b32_e32 v65, 0xffff0000, v59
	v_add_f32_e32 v46, v46, v64
	v_add_f32_e32 v47, v47, v65
	v_lshlrev_b32_e32 v64, 16, v60
	v_and_b32_e32 v65, 0xffff0000, v60
	v_add_f32_e32 v48, v48, v64
	v_add_f32_e32 v49, v49, v65
	v_lshlrev_b32_e32 v64, 16, v61
	v_and_b32_e32 v65, 0xffff0000, v61
	v_add_f32_e32 v50, v50, v64
	v_add_f32_e32 v51, v51, v65
	v_lshlrev_b32_e32 v64, 16, v62
	v_and_b32_e32 v65, 0xffff0000, v62
	v_add_f32_e32 v52, v52, v64
	v_add_f32_e32 v53, v53, v65
	v_lshlrev_b32_e32 v64, 16, v63
	v_and_b32_e32 v65, 0xffff0000, v63
	v_add_f32_e32 v54, v54, v64
	v_add_f32_e32 v55, v55, v65
	v_mul_f32_e32 v64, v40, v40
	v_mul_f32_e32 v65, v41, v41
	v_mul_f32_e32 v66, v42, v42
	v_mul_f32_e32 v67, v43, v43
	v_add_f32_e32 v64, v64, v65
	v_add_f32_e32 v66, v66, v67
	v_add_f32_e32 v68, v64, v66
	v_mul_f32_e32 v64, v44, v44
	v_mul_f32_e32 v65, v45, v45
	v_mul_f32_e32 v66, v46, v46
	v_mul_f32_e32 v67, v47, v47
	v_add_f32_e32 v64, v64, v65
	v_add_f32_e32 v66, v66, v67
	v_add_f32_e32 v64, v64, v66
	v_add_f32_e32 v68, v68, v64
	v_mul_f32_e32 v64, v48, v48
	v_mul_f32_e32 v65, v49, v49
	v_mul_f32_e32 v66, v50, v50
	v_mul_f32_e32 v67, v51, v51
	v_add_f32_e32 v64, v64, v65
	v_add_f32_e32 v66, v66, v67
	v_add_f32_e32 v64, v64, v66
	v_add_f32_e32 v68, v68, v64
	v_mul_f32_e32 v64, v52, v52
	v_mul_f32_e32 v65, v53, v53
	v_mul_f32_e32 v66, v54, v54
	v_mul_f32_e32 v67, v55, v55
	v_add_f32_e32 v64, v64, v65
	v_add_f32_e32 v66, v66, v67
	v_add_f32_e32 v64, v64, v66
	v_add_f32_e32 v68, v68, v64
	ds_bpermute_b32 v69, v72, v68
	s_waitcnt lgkmcnt(0)
	v_add_f32_e32 v68, v68, v69
	ds_bpermute_b32 v69, v73, v68
	s_waitcnt lgkmcnt(0)
; __device__ __forceinline__ void phase4(const Params& P, int lane, int wave) {
;     ...
;         ss = wave_sum(ss);
;         const float rstd = 1.0f / sqrtf(ss * (1.0f / 1024.0f) + RMS_EPS);
;         float* row = P.out + (size_t)m * 1024;
; #pragma unroll
;         for (int j = 0; j < 4; ++j) *(f32x4*)(row + 4 * lane + 256 * j) = r[j] * rstd * g4[j];
;     }
	v_add_f32_e32 v68, v68, v69
	ds_bpermute_b32 v69, v74, v68
	s_waitcnt lgkmcnt(0)
	v_add_f32_e32 v68, v68, v69
	ds_bpermute_b32 v69, v75, v68
	s_waitcnt lgkmcnt(0)
	v_add_f32_e32 v68, v68, v69
	ds_bpermute_b32 v69, v76, v68
	s_waitcnt lgkmcnt(0)
	v_add_f32_e32 v68, v68, v69
	ds_bpermute_b32 v69, v77, v68
	s_waitcnt lgkmcnt(0)
	v_add_f32_e32 v68, v68, v69
	v_fmamk_f32 v68, v68, 0x3a800000, v70
	v_mul_f32_e32 v69, 0x4f800000, v68
	v_cmp_gt_f32_e32 vcc, s2, v68
	s_nop 1
	v_cndmask_b32_e32 v68, v68, v69, vcc
	v_sqrt_f32_e32 v69, v68
	s_nop 0
	v_add_u32_e32 v64, -1, v69
	v_fma_f32 v65, -v64, v69, v68
	v_cmp_ge_f32_e64 s[6:7], 0, v65
	v_add_u32_e32 v65, 1, v69
	s_nop 0
	v_cndmask_b32_e64 v64, v69, v64, s[6:7]
	v_fma_f32 v69, -v65, v69, v68
	v_cmp_lt_f32_e64 s[6:7], 0, v69
	s_nop 1
	v_cndmask_b32_e64 v69, v64, v65, s[6:7]
	v_mul_f32_e32 v64, 0x37800000, v69
	v_cndmask_b32_e32 v69, v69, v64, vcc
	v_cmp_class_f32_e32 vcc, v68, v71
	s_nop 1
	v_cndmask_b32_e32 v68, v69, v68, vcc
	v_div_scale_f32 v69, s[6:7], v68, v68, 1.0
	v_rcp_f32_e32 v64, v69
	s_nop 0
	v_fma_f32 v65, -v69, v64, 1.0
	v_fmac_f32_e32 v64, v65, v64
	v_div_scale_f32 v65, vcc, 1.0, v68, 1.0
	v_mul_f32_e32 v66, v65, v64
	v_fma_f32 v67, -v69, v66, v65
	v_fmac_f32_e32 v66, v67, v64
	v_fma_f32 v69, -v69, v66, v65
	v_div_fmas_f32 v69, v69, v64, v66
	v_div_fixup_f32 v68, v69, v68, 1.0
	v_mul_f32_e32 v40, v40, v68
	v_mul_f32_e32 v41, v41, v68
	v_mul_f32_e32 v42, v42, v68
	v_mul_f32_e32 v43, v43, v68
	v_mul_f32_e32 v40, v0, v40
	v_mul_f32_e32 v41, v1, v41
	v_mul_f32_e32 v42, v2, v42
	v_mul_f32_e32 v43, v3, v43
	global_store_dwordx4 v80, v[40:43], s[0:1]
	v_mul_f32_e32 v44, v44, v68
	v_mul_f32_e32 v45, v45, v68
	v_mul_f32_e32 v46, v46, v68
	v_mul_f32_e32 v47, v47, v68
	v_mul_f32_e32 v44, v4, v44
	v_mul_f32_e32 v45, v5, v45
	v_mul_f32_e32 v46, v6, v46
	v_mul_f32_e32 v47, v7, v47
	global_store_dwordx4 v80, v[44:47], s[0:1] offset:1024
	v_mul_f32_e32 v48, v48, v68
	v_mul_f32_e32 v49, v49, v68
	v_mul_f32_e32 v50, v50, v68
	v_mul_f32_e32 v51, v51, v68
	v_mul_f32_e32 v48, v8, v48
	v_mul_f32_e32 v49, v9, v49
	v_mul_f32_e32 v50, v10, v50
	v_mul_f32_e32 v51, v11, v51
	global_store_dwordx4 v80, v[48:51], s[0:1] offset:2048
	v_mul_f32_e32 v52, v52, v68
	v_mul_f32_e32 v53, v53, v68
	v_mul_f32_e32 v54, v54, v68
	v_mul_f32_e32 v55, v55, v68
	v_mul_f32_e32 v52, v12, v52
	v_mul_f32_e32 v53, v13, v53
	v_mul_f32_e32 v54, v14, v54
	v_mul_f32_e32 v55, v15, v55
	global_store_dwordx4 v80, v[52:55], s[0:1] offset:3072
	s_add_i32 s11, s11, s84
	s_cmp_ge_u32 s11, 0x10100
	s_cbranch_scc1 .LBB0_806
; __device__ __forceinline__ float bf_lo(unsigned w) { return __uint_as_float(w << 16); }
; __device__ __forceinline__ float bf_hi(unsigned w) { return __uint_as_float(w & 0xffff0000u); }
; __device__ __forceinline__ void phase4(const Params& P, int lane, int wave) {
;     ...
;     for (; m < MT; m += NGW) {
;         f32x4 r[4]; float ss = 0.f;
; #pragma unroll
;         for (int j = 0; j < 4; ++j) {
;             r[j][0] = v[j][0] + bf_lo(mv[j].x); r[j][1] = v[j][1] + bf_hi(mv[j].x); r[j][2] = v[j][2] + bf_lo(mv[j].y); r[j][3] = v[j][3] + bf_hi(mv[j].y);
;             ss += (r[j][0] * r[j][0] + r[j][1] * r[j][1]) + (r[j][2] * r[j][2] + r[j][3] * r[j][3]);
;         }
;         const int mn = m + NGW;
;         if (mn < MT) {
;             const float* xrow = (mn < MP) ? P.xp + (size_t)mn * 1024 : P.xs + (size_t)(mn - MP) * 1024;
; #pragma unroll
;             for (int j = 0; j < 4; ++j) { v[j] = *(const f32x4*)(xrow + 4 * lane + 256 * j); mv[j] = *(const u32x2*)(mo + (size_t)mn * 1024 + 4 * lane + 256 * j); }
;         }
;         ss = wave_sum(ss);
;         const float rstd = 1.0f / sqrtf(ss * (1.0f / 1024.0f) + RMS_EPS);
;         float* row = P.out + (size_t)m * 1024;
; #pragma unroll
;         for (int j = 0; j < 4; ++j) *(f32x4*)(row + 4 * lane + 256 * j) = r[j] * rstd * g4[j];
;     }
	s_lshl_b32 s20, s84, 1
	s_add_i32 s20, s11, s20
	s_cmp_lt_u32 s20, 0x10100
	s_cselect_b32 s20, s20, s11
	s_mov_b32 s16, s20
	s_lshl_b32 s17, s16, 11
	s_add_u32 s14, s4, s17
	s_addc_u32 s15, s5, 0
	s_add_i32 s18, s16, 0xffff0000
	s_cmp_lt_u32 s16, 0x10000
	s_cselect_b32 s18, s16, s18
	s_cselect_b32 s12, s68, s70
	s_cselect_b32 s13, s69, s71
	s_lshr_b32 s19, s18, 20
	s_lshl_b32 s18, s18, 12
	s_add_u32 s12, s12, s18
	s_addc_u32 s13, s13, s19
	global_load_dwordx4 v[40:43], v80, s[12:13]
	global_load_dwordx4 v[44:47], v80, s[12:13] offset:1024
	global_load_dwordx4 v[48:51], v80, s[12:13] offset:2048
	global_load_dwordx4 v[52:55], v80, s[12:13] offset:3072
	global_load_dwordx2 v[56:57], v81, s[14:15]
	global_load_dwordx2 v[58:59], v81, s[14:15] offset:512
	global_load_dwordx2 v[60:61], v81, s[14:15] offset:1024
	global_load_dwordx2 v[62:63], v81, s[14:15] offset:1536
	s_lshr_b32 s19, s11, 20
	s_lshl_b32 s18, s11, 12
	s_add_u32 s0, s90, s18
	s_addc_u32 s1, s91, s19
	s_waitcnt vmcnt(16)
	v_lshlrev_b32_e32 v64, 16, v104
	v_and_b32_e32 v65, 0xffff0000, v104
	v_add_f32_e32 v88, v88, v64
	v_add_f32_e32 v89, v89, v65
	v_lshlrev_b32_e32 v64, 16, v105
	v_and_b32_e32 v65, 0xffff0000, v105
	v_add_f32_e32 v90, v90, v64
	v_add_f32_e32 v91, v91, v65
	v_lshlrev_b32_e32 v64, 16, v106
	v_and_b32_e32 v65, 0xffff0000, v106
	v_add_f32_e32 v92, v92, v64
	v_add_f32_e32 v93, v93, v65
	v_lshlrev_b32_e32 v64, 16, v107
	v_and_b32_e32 v65, 0xffff0000, v107
	v_add_f32_e32 v94, v94, v64
	v_add_f32_e32 v95, v95, v65
	v_lshlrev_b32_e32 v64, 16, v108
	v_and_b32_e32 v65, 0xffff0000, v108
	v_add_f32_e32 v96, v96, v64
	v_add_f32_e32 v97, v97, v65
	v_lshlrev_b32_e32 v64, 16, v109
	v_and_b32_e32 v65, 0xffff0000, v109
	v_add_f32_e32 v98, v98, v64
	v_add_f32_e32 v99, v99, v65
	v_lshlrev_b32_e32 v64, 16, v110
	v_and_b32_e32 v65, 0xffff0000, v110
	v_add_f32_e32 v100, v100, v64
	v_add_f32_e32 v101, v101, v65
	v_lshlrev_b32_e32 v64, 16, v111
	v_and_b32_e32 v65, 0xffff0000, v111
	v_add_f32_e32 v102, v102, v64
	v_add_f32_e32 v103, v103, v65
	v_mul_f32_e32 v64, v88, v88
	v_mul_f32_e32 v65, v89, v89
	v_mul_f32_e32 v66, v90, v90
	v_mul_f32_e32 v67, v91, v91
	v_add_f32_e32 v64, v64, v65
	v_add_f32_e32 v66, v66, v67
	v_add_f32_e32 v68, v64, v66
	v_mul_f32_e32 v64, v92, v92
	v_mul_f32_e32 v65, v93, v93
	v_mul_f32_e32 v66, v94, v94
	v_mul_f32_e32 v67, v95, v95
	v_add_f32_e32 v64, v64, v65
	v_add_f32_e32 v66, v66, v67
	v_add_f32_e32 v64, v64, v66
	v_add_f32_e32 v68, v68, v64
	v_mul_f32_e32 v64, v96, v96
	v_mul_f32_e32 v65, v97, v97
	v_mul_f32_e32 v66, v98, v98
	v_mul_f32_e32 v67, v99, v99
	v_add_f32_e32 v64, v64, v65
	v_add_f32_e32 v66, v66, v67
	v_add_f32_e32 v64, v64, v66
	v_add_f32_e32 v68, v68, v64
	v_mul_f32_e32 v64, v100, v100
	v_mul_f32_e32 v65, v101, v101
	v_mul_f32_e32 v66, v102, v102
	v_mul_f32_e32 v67, v103, v103
	v_add_f32_e32 v64, v64, v65
	v_add_f32_e32 v66, v66, v67
	v_add_f32_e32 v64, v64, v66
	v_add_f32_e32 v68, v68, v64
	ds_bpermute_b32 v69, v72, v68
	s_waitcnt lgkmcnt(0)
	v_add_f32_e32 v68, v68, v69
	ds_bpermute_b32 v69, v73, v68
	s_waitcnt lgkmcnt(0)
	v_add_f32_e32 v68, v68, v69
	ds_bpermute_b32 v69, v74, v68
	s_waitcnt lgkmcnt(0)
	v_add_f32_e32 v68, v68, v69
	ds_bpermute_b32 v69, v75, v68
	s_waitcnt lgkmcnt(0)
	v_add_f32_e32 v68, v68, v69
	ds_bpermute_b32 v69, v76, v68
	s_waitcnt lgkmcnt(0)
	v_add_f32_e32 v68, v68, v69
	ds_bpermute_b32 v69, v77, v68
	s_waitcnt lgkmcnt(0)
	v_add_f32_e32 v68, v68, v69
	v_fmamk_f32 v68, v68, 0x3a800000, v70
	v_mul_f32_e32 v69, 0x4f800000, v68
	v_cmp_gt_f32_e32 vcc, s2, v68
	s_nop 1
	v_cndmask_b32_e32 v68, v68, v69, vcc
	v_sqrt_f32_e32 v69, v68
	s_nop 0
	v_add_u32_e32 v64, -1, v69
	v_fma_f32 v65, -v64, v69, v68
	v_cmp_ge_f32_e64 s[6:7], 0, v65
	v_add_u32_e32 v65, 1, v69
	s_nop 0
	v_cndmask_b32_e64 v64, v69, v64, s[6:7]
	v_fma_f32 v69, -v65, v69, v68
	v_cmp_lt_f32_e64 s[6:7], 0, v69
	s_nop 1
	v_cndmask_b32_e64 v69, v64, v65, s[6:7]
	v_mul_f32_e32 v64, 0x37800000, v69
	v_cndmask_b32_e32 v69, v69, v64, vcc
	v_cmp_class_f32_e32 vcc, v68, v71
	s_nop 1
	v_cndmask_b32_e32 v68, v69, v68, vcc
	v_div_scale_f32 v69, s[6:7], v68, v68, 1.0
	v_rcp_f32_e32 v64, v69
	s_nop 0
	v_fma_f32 v65, -v69, v64, 1.0
	v_fmac_f32_e32 v64, v65, v64
	v_div_scale_f32 v65, vcc, 1.0, v68, 1.0
	v_mul_f32_e32 v66, v65, v64
	v_fma_f32 v67, -v69, v66, v65
	v_fmac_f32_e32 v66, v67, v64
	v_fma_f32 v69, -v69, v66, v65
	v_div_fmas_f32 v69, v69, v64, v66
	v_div_fixup_f32 v68, v69, v68, 1.0
	v_mul_f32_e32 v88, v88, v68
	v_mul_f32_e32 v89, v89, v68
	v_mul_f32_e32 v90, v90, v68
	v_mul_f32_e32 v91, v91, v68
	v_mul_f32_e32 v88, v0, v88
	v_mul_f32_e32 v89, v1, v89
	v_mul_f32_e32 v90, v2, v90
	v_mul_f32_e32 v91, v3, v91
	global_store_dwordx4 v80, v[88:91], s[0:1]
	v_mul_f32_e32 v92, v92, v68
	v_mul_f32_e32 v93, v93, v68
	v_mul_f32_e32 v94, v94, v68
	v_mul_f32_e32 v95, v95, v68
	v_mul_f32_e32 v92, v4, v92
	v_mul_f32_e32 v93, v5, v93
	v_mul_f32_e32 v94, v6, v94
	v_mul_f32_e32 v95, v7, v95
	global_store_dwordx4 v80, v[92:95], s[0:1] offset:1024
	v_mul_f32_e32 v96, v96, v68
	v_mul_f32_e32 v97, v97, v68
	v_mul_f32_e32 v98, v98, v68
	v_mul_f32_e32 v99, v99, v68
	v_mul_f32_e32 v96, v8, v96
	v_mul_f32_e32 v97, v9, v97
	v_mul_f32_e32 v98, v10, v98
	v_mul_f32_e32 v99, v11, v99
	global_store_dwordx4 v80, v[96:99], s[0:1] offset:2048
	v_mul_f32_e32 v100, v100, v68
	v_mul_f32_e32 v101, v101, v68
	v_mul_f32_e32 v102, v102, v68
	v_mul_f32_e32 v103, v103, v68
	v_mul_f32_e32 v100, v12, v100
	v_mul_f32_e32 v101, v13, v101
	v_mul_f32_e32 v102, v14, v102
	v_mul_f32_e32 v103, v15, v103
	global_store_dwordx4 v80, v[100:103], s[0:1] offset:3072
	s_add_i32 s11, s11, s84
	s_cmp_ge_u32 s11, 0x10100
	s_cbranch_scc1 .LBB0_806
	s_branch .Lp4_loop
